# the five GEMM main loops pinned to 64-byte boundaries (.p2align 6) so their placement no longer moves with edits above them
# baseline (speedup 1.0000x reference)
; template <class Epi, class Sched, bool ALIGN_EPI = false, bool SP2 = false>
; __device__ __forceinline__ void gemm_phase(LAS unsigned char* lds, const Gemm g, const Sched& S, const Epi& E, const int tid) {
;     ...
;     for (;;) {
;         const bool has_next = S.next(ui + 1, nxt);
;         const char* nA = has_next ? (const char*)g.A + (size_t)nxt.pm * tstep : cA; const char* nB = has_next ? (const char*)g.Bt + (size_t)nxt.pn * tstep : cB;
;         for (int t = 0; t < nt; t += 2) {
;             const bool last = (t == nt - 2);
;             const char* a1 = cA + (size_t)(t + 1) * kstep;
;             const char* a2 = last ? nA : cA + (size_t)(t + 2) * kstep; const char* b2 = last ? nB : cB + (size_t)(t + 2) * kstep;
;     ...
; #pragma unroll
;         for (int a = 0; a < 2; ++a)
; #pragma unroll
;             for (int b = 0; b < 2; ++b)
; #pragma unroll
;                 for (int m = 0; m < 4; ++m)
; #pragma unroll
;                     for (int n = 0; n < 2; ++n) acc[a][b][m][n] = (f32x4){0.f, 0.f, 0.f, 0.f};
;         cur = nxt; cA = nA; cB = nB; ++ui;
.LBB0_366:
	s_ashr_i32 s31, s30, 31
	s_lshl_b64 s[0:1], s[30:31], 20
	s_add_u32 s34, s46, s0
	s_addc_u32 s35, s47, s1
	s_and_b64 s[0:1], s[2:3], exec
	s_cselect_b32 s7, s35, s39
	s_cselect_b32 s9, s34, s38
	s_ashr_i32 s29, s28, 31
	s_lshl_b64 s[0:1], s[28:29], 20
	s_add_u32 s36, s48, s0
	s_addc_u32 s37, s49, s1
	s_and_b64 s[0:1], s[2:3], exec
	s_cselect_b32 s29, s37, s5
	s_cselect_b32 s31, s36, s4
	s_add_u32 s0, s38, 0x80080
	s_addc_u32 s1, s39, 0
	s_add_u32 s61, s4, 0x100
	v_mov_b32_e32 v0, 0
	s_addc_u32 s62, s5, 0
	s_mov_b32 s63, -2
	v_mov_b32_e32 v1, v0
	v_mov_b32_e32 v2, v0
	v_mov_b32_e32 v3, v0
	v_mov_b32_e32 v4, v0
	v_mov_b32_e32 v5, v0
	v_mov_b32_e32 v6, v0
	v_mov_b32_e32 v7, v0
	v_mov_b32_e32 v16, v0
	v_mov_b32_e32 v17, v0
	v_mov_b32_e32 v18, v0
	v_mov_b32_e32 v19, v0
	v_mov_b32_e32 v20, v0
	v_mov_b32_e32 v21, v0
	v_mov_b32_e32 v22, v0
	v_mov_b32_e32 v23, v0
	v_mov_b32_e32 v32, v0
	v_mov_b32_e32 v33, v0
	v_mov_b32_e32 v34, v0
	v_mov_b32_e32 v35, v0
	v_mov_b32_e32 v36, v0
	v_mov_b32_e32 v37, v0
	v_mov_b32_e32 v38, v0
	v_mov_b32_e32 v39, v0
	v_mov_b32_e32 v48, v0
	v_mov_b32_e32 v49, v0
	v_mov_b32_e32 v50, v0
	v_mov_b32_e32 v51, v0
	v_mov_b32_e32 v52, v0
	v_mov_b32_e32 v53, v0
	v_mov_b32_e32 v54, v0
	v_mov_b32_e32 v55, v0
	v_mov_b32_e32 v8, v0
	v_mov_b32_e32 v9, v0
	v_mov_b32_e32 v10, v0
	v_mov_b32_e32 v11, v0
	v_mov_b32_e32 v12, v0
	v_mov_b32_e32 v13, v0
	v_mov_b32_e32 v14, v0
	v_mov_b32_e32 v15, v0
	v_mov_b32_e32 v24, v0
	v_mov_b32_e32 v25, v0
	v_mov_b32_e32 v26, v0
	v_mov_b32_e32 v27, v0
	v_mov_b32_e32 v28, v0
	v_mov_b32_e32 v29, v0
	v_mov_b32_e32 v30, v0
	v_mov_b32_e32 v31, v0
	v_mov_b32_e32 v40, v0
	v_mov_b32_e32 v41, v0
	v_mov_b32_e32 v42, v0
	v_mov_b32_e32 v43, v0
	v_mov_b32_e32 v44, v0
	v_mov_b32_e32 v45, v0
	v_mov_b32_e32 v46, v0
	v_mov_b32_e32 v47, v0
	v_mov_b32_e32 v56, v0
	v_mov_b32_e32 v57, v0
	v_mov_b32_e32 v58, v0
	v_mov_b32_e32 v59, v0
	v_mov_b32_e32 v60, v0
	v_mov_b32_e32 v61, v0
	v_mov_b32_e32 v62, v0
	v_mov_b32_e32 v63, v0
	v_mov_b32_e32 v64, v0
	v_mov_b32_e32 v65, v0
	v_mov_b32_e32 v66, v0
	v_mov_b32_e32 v67, v0
	v_mov_b32_e32 v68, v0
	v_mov_b32_e32 v69, v0
	v_mov_b32_e32 v70, v0
	v_mov_b32_e32 v71, v0
	v_mov_b32_e32 v80, v0
	v_mov_b32_e32 v81, v0
	v_mov_b32_e32 v82, v0
	v_mov_b32_e32 v83, v0
	v_mov_b32_e32 v84, v0
	v_mov_b32_e32 v85, v0
	v_mov_b32_e32 v86, v0
	v_mov_b32_e32 v87, v0
	v_mov_b32_e32 v96, v0
	v_mov_b32_e32 v97, v0
	v_mov_b32_e32 v98, v0
	v_mov_b32_e32 v99, v0
	v_mov_b32_e32 v100, v0
	v_mov_b32_e32 v101, v0
	v_mov_b32_e32 v102, v0
	v_mov_b32_e32 v103, v0
	v_mov_b32_e32 v112, v0
	v_mov_b32_e32 v113, v0
	v_mov_b32_e32 v114, v0
	v_mov_b32_e32 v115, v0
	v_mov_b32_e32 v116, v0
	v_mov_b32_e32 v117, v0
	v_mov_b32_e32 v118, v0
	v_mov_b32_e32 v119, v0
	v_mov_b32_e32 v72, v0
	v_mov_b32_e32 v73, v0
	v_mov_b32_e32 v74, v0
	v_mov_b32_e32 v75, v0
	v_mov_b32_e32 v76, v0
	v_mov_b32_e32 v77, v0
	v_mov_b32_e32 v78, v0
	v_mov_b32_e32 v79, v0
	v_mov_b32_e32 v88, v0
	v_mov_b32_e32 v89, v0
	v_mov_b32_e32 v90, v0
	v_mov_b32_e32 v91, v0
	v_mov_b32_e32 v92, v0
	v_mov_b32_e32 v93, v0
	v_mov_b32_e32 v94, v0
	v_mov_b32_e32 v95, v0
	v_mov_b32_e32 v104, v0
	v_mov_b32_e32 v105, v0
	v_mov_b32_e32 v106, v0
	v_mov_b32_e32 v107, v0
	v_mov_b32_e32 v108, v0
	v_mov_b32_e32 v109, v0
	v_mov_b32_e32 v110, v0
	v_mov_b32_e32 v111, v0
	v_mov_b32_e32 v120, v0
	v_mov_b32_e32 v121, v0
	v_mov_b32_e32 v122, v0
	v_mov_b32_e32 v123, v0
	v_mov_b32_e32 v124, v0
	v_mov_b32_e32 v125, v0
	v_mov_b32_e32 v126, v0
	v_mov_b32_e32 v127, v0
	.p2align 6

; template <class Epi, class Sched, bool ALIGN_EPI = false, bool SP2 = false>
; __device__ __forceinline__ void gemm_phase(LAS unsigned char* lds, const Gemm g, const Sched& S, const Epi& E, const int tid) {
;     ...
;     for (;;) {
;         const bool has_next = S.next(ui + 1, nxt);
;         const char* nA = has_next ? (const char*)g.A + (size_t)nxt.pm * tstep : cA; const char* nB = has_next ? (const char*)g.Bt + (size_t)nxt.pn * tstep : cB;
;         for (int t = 0; t < nt; t += 2) {
;             const bool last = (t == nt - 2);
;             const char* a1 = cA + (size_t)(t + 1) * kstep;
;             const char* a2 = last ? nA : cA + (size_t)(t + 2) * kstep; const char* b2 = last ? nB : cB + (size_t)(t + 2) * kstep;
;     ...
; #pragma unroll
;         for (int a = 0; a < 2; ++a)
; #pragma unroll
;             for (int b = 0; b < 2; ++b)
; #pragma unroll
;                 for (int m = 0; m < 4; ++m)
; #pragma unroll
;                     for (int n = 0; n < 2; ++n) acc[a][b][m][n] = (f32x4){0.f, 0.f, 0.f, 0.f};
;         cur = nxt; cA = nA; cB = nB; ++ui;
.LBB0_1314:
	s_ashr_i32 s17, s16, 31
	s_lshl_b64 s[18:19], s[16:17], 19
	s_add_u32 s18, s31, s18
	s_addc_u32 s19, s34, s19
	s_and_b64 s[20:21], s[2:3], exec
	s_cselect_b32 s17, s19, s23
	s_cselect_b32 s46, s18, s22
	s_ashr_i32 s15, s14, 31
	s_lshl_b64 s[20:21], s[14:15], 19
	s_add_u32 s20, s35, s20
	s_addc_u32 s21, s36, s21
	s_and_b64 s[26:27], s[2:3], exec
	s_cselect_b32 s15, s21, s25
	s_cselect_b32 s47, s20, s24
	s_add_u32 s22, s22, 0x40080
	s_addc_u32 s23, s23, 0
	s_add_u32 s48, s24, 0x100
	v_mov_b32_e32 v4, 0
	s_addc_u32 s49, s25, 0
	s_mov_b32 s50, -2
	v_mov_b32_e32 v5, v4
	v_mov_b32_e32 v6, v4
	v_mov_b32_e32 v7, v4
	v_mov_b32_e32 v0, v4
	v_mov_b32_e32 v1, v4
	v_mov_b32_e32 v2, v4
	v_mov_b32_e32 v3, v4
	v_mov_b32_e32 v20, v4
	v_mov_b32_e32 v21, v4
	v_mov_b32_e32 v22, v4
	v_mov_b32_e32 v23, v4
	v_mov_b32_e32 v16, v4
	v_mov_b32_e32 v17, v4
	v_mov_b32_e32 v18, v4
	v_mov_b32_e32 v19, v4
	v_mov_b32_e32 v36, v4
	v_mov_b32_e32 v37, v4
	v_mov_b32_e32 v38, v4
	v_mov_b32_e32 v39, v4
	v_mov_b32_e32 v32, v4
	v_mov_b32_e32 v33, v4
	v_mov_b32_e32 v34, v4
	v_mov_b32_e32 v35, v4
	v_mov_b32_e32 v52, v4
	v_mov_b32_e32 v53, v4
	v_mov_b32_e32 v54, v4
	v_mov_b32_e32 v55, v4
	v_mov_b32_e32 v48, v4
	v_mov_b32_e32 v49, v4
	s_waitcnt vmcnt(0)
	v_mov_b32_e32 v50, v4
	v_mov_b32_e32 v51, v4
	v_mov_b32_e32 v8, v4
	v_mov_b32_e32 v9, v4
	v_mov_b32_e32 v10, v4
	v_mov_b32_e32 v11, v4
	v_mov_b32_e32 v12, v4
	v_mov_b32_e32 v13, v4
	v_mov_b32_e32 v14, v4
	v_mov_b32_e32 v15, v4
	v_mov_b32_e32 v24, v4
	v_mov_b32_e32 v25, v4
	v_mov_b32_e32 v26, v4
	v_mov_b32_e32 v27, v4
	v_mov_b32_e32 v28, v4
	v_mov_b32_e32 v29, v4
	v_mov_b32_e32 v30, v4
	v_mov_b32_e32 v31, v4
	v_mov_b32_e32 v40, v4
	v_mov_b32_e32 v41, v4
	v_mov_b32_e32 v42, v4
	v_mov_b32_e32 v43, v4
	v_mov_b32_e32 v44, v4
	v_mov_b32_e32 v45, v4
	v_mov_b32_e32 v46, v4
	v_mov_b32_e32 v47, v4
	v_mov_b32_e32 v56, v4
	v_mov_b32_e32 v57, v4
	v_mov_b32_e32 v58, v4
	v_mov_b32_e32 v59, v4
	v_mov_b32_e32 v60, v4
	v_mov_b32_e32 v61, v4
	v_mov_b32_e32 v62, v4
	v_mov_b32_e32 v63, v4
	v_mov_b32_e32 v68, v4
	v_mov_b32_e32 v69, v4
	v_mov_b32_e32 v70, v4
	v_mov_b32_e32 v71, v4
	v_mov_b32_e32 v64, v4
	v_mov_b32_e32 v65, v4
	v_mov_b32_e32 v66, v4
	v_mov_b32_e32 v67, v4
	v_mov_b32_e32 v100, v4
	v_mov_b32_e32 v101, v4
	v_mov_b32_e32 v102, v4
	v_mov_b32_e32 v103, v4
	v_mov_b32_e32 v96, v4
	v_mov_b32_e32 v97, v4
	v_mov_b32_e32 v98, v4
	v_mov_b32_e32 v99, v4
	v_mov_b32_e32 v116, v4
	v_mov_b32_e32 v117, v4
	v_mov_b32_e32 v118, v4
	v_mov_b32_e32 v119, v4
	v_mov_b32_e32 v112, v4
	v_mov_b32_e32 v113, v4
	v_mov_b32_e32 v114, v4
	v_mov_b32_e32 v115, v4
	v_mov_b32_e32 v128, v4
	v_mov_b32_e32 v129, v4
	v_mov_b32_e32 v130, v4
	v_mov_b32_e32 v131, v4
	v_mov_b32_e32 v132, v4
	v_mov_b32_e32 v133, v4
	v_mov_b32_e32 v134, v4
	v_mov_b32_e32 v135, v4
	v_mov_b32_e32 v80, v4
	v_mov_b32_e32 v81, v4
	v_mov_b32_e32 v82, v4
	v_mov_b32_e32 v83, v4
	v_mov_b32_e32 v84, v4
	v_mov_b32_e32 v85, v4
	v_mov_b32_e32 v86, v4
	v_mov_b32_e32 v87, v4
	v_mov_b32_e32 v104, v4
	v_mov_b32_e32 v105, v4
	v_mov_b32_e32 v106, v4
	v_mov_b32_e32 v107, v4
	v_mov_b32_e32 v108, v4
	v_mov_b32_e32 v109, v4
	v_mov_b32_e32 v110, v4
	v_mov_b32_e32 v111, v4
	v_mov_b32_e32 v120, v4
	v_mov_b32_e32 v121, v4
	v_mov_b32_e32 v122, v4
	v_mov_b32_e32 v123, v4
	v_mov_b32_e32 v124, v4
	v_mov_b32_e32 v125, v4
	v_mov_b32_e32 v126, v4
	v_mov_b32_e32 v127, v4
	v_mov_b32_e32 v136, v4
	v_mov_b32_e32 v137, v4
	v_mov_b32_e32 v138, v4
	v_mov_b32_e32 v139, v4
	v_mov_b32_e32 v140, v4
	v_mov_b32_e32 v141, v4
	v_mov_b32_e32 v142, v4
	v_mov_b32_e32 v143, v4
	.p2align 6

; template <class Epi, class Sched, bool ALIGN_EPI = false, bool SP2 = false>
; __device__ __forceinline__ void gemm_phase(LAS unsigned char* lds, const Gemm g, const Sched& S, const Epi& E, const int tid) {
;     ...
;     for (;;) {
;         const bool has_next = S.next(ui + 1, nxt);
;         const char* nA = has_next ? (const char*)g.A + (size_t)nxt.pm * tstep : cA; const char* nB = has_next ? (const char*)g.Bt + (size_t)nxt.pn * tstep : cB;
;         for (int t = 0; t < nt; t += 2) {
;             const bool last = (t == nt - 2);
;             const char* a1 = cA + (size_t)(t + 1) * kstep;
;             const char* a2 = last ? nA : cA + (size_t)(t + 2) * kstep; const char* b2 = last ? nB : cB + (size_t)(t + 2) * kstep;
;     ...
; #pragma unroll
;         for (int a = 0; a < 2; ++a)
; #pragma unroll
;             for (int b = 0; b < 2; ++b)
; #pragma unroll
;                 for (int m = 0; m < 4; ++m)
; #pragma unroll
;                     for (int n = 0; n < 2; ++n) acc[a][b][m][n] = (f32x4){0.f, 0.f, 0.f, 0.f};
;         cur = nxt; cA = nA; cB = nB; ++ui;
.LBB0_1354:
	s_ashr_i32 s15, s14, 31
	s_lshl_b64 s[16:17], s[14:15], 20
	s_add_u32 s16, s34, s16
	s_addc_u32 s17, s35, s17
	s_and_b64 s[18:19], s[4:5], exec
	s_cselect_b32 s1, s17, s23
	s_cselect_b32 s15, s16, s22
	s_ashr_i32 s13, s12, 31
	s_lshl_b64 s[18:19], s[12:13], 20
	s_add_u32 s18, s36, s18
	s_addc_u32 s19, s37, s19
	s_and_b64 s[26:27], s[4:5], exec
	s_cselect_b32 s13, s19, s25
	s_cselect_b32 s21, s18, s24
	s_add_u32 s51, s24, 0x100
	v_mov_b32_e32 v0, 0
	s_addc_u32 s52, s25, 0
	s_mov_b32 s53, -2
	s_waitcnt lgkmcnt(0)
	v_mov_b32_e32 v1, v0
	v_mov_b32_e32 v2, v0
	v_mov_b32_e32 v3, v0
	v_mov_b32_e32 v4, v0
	v_mov_b32_e32 v5, v0
	v_mov_b32_e32 v6, v0
	v_mov_b32_e32 v7, v0
	v_mov_b32_e32 v16, v0
	v_mov_b32_e32 v17, v0
	v_mov_b32_e32 v18, v0
	v_mov_b32_e32 v19, v0
	v_mov_b32_e32 v20, v0
	v_mov_b32_e32 v21, v0
	v_mov_b32_e32 v22, v0
	v_mov_b32_e32 v23, v0
	v_mov_b32_e32 v32, v0
	v_mov_b32_e32 v33, v0
	v_mov_b32_e32 v34, v0
	v_mov_b32_e32 v35, v0
	v_mov_b32_e32 v36, v0
	v_mov_b32_e32 v37, v0
	v_mov_b32_e32 v38, v0
	v_mov_b32_e32 v39, v0
	v_mov_b32_e32 v48, v0
	v_mov_b32_e32 v49, v0
	s_waitcnt vmcnt(0)
	v_mov_b32_e32 v50, v0
	v_mov_b32_e32 v51, v0
	v_mov_b32_e32 v52, v0
	v_mov_b32_e32 v53, v0
	v_mov_b32_e32 v54, v0
	v_mov_b32_e32 v55, v0
	v_mov_b32_e32 v8, v0
	v_mov_b32_e32 v9, v0
	v_mov_b32_e32 v10, v0
	v_mov_b32_e32 v11, v0
	v_mov_b32_e32 v12, v0
	v_mov_b32_e32 v13, v0
	v_mov_b32_e32 v14, v0
	v_mov_b32_e32 v15, v0
	v_mov_b32_e32 v24, v0
	v_mov_b32_e32 v25, v0
	v_mov_b32_e32 v26, v0
	v_mov_b32_e32 v27, v0
	v_mov_b32_e32 v28, v0
	v_mov_b32_e32 v29, v0
	v_mov_b32_e32 v30, v0
	v_mov_b32_e32 v31, v0
	v_mov_b32_e32 v40, v0
	v_mov_b32_e32 v41, v0
	v_mov_b32_e32 v42, v0
	v_mov_b32_e32 v43, v0
	v_mov_b32_e32 v44, v0
	v_mov_b32_e32 v45, v0
	v_mov_b32_e32 v46, v0
	v_mov_b32_e32 v47, v0
	v_mov_b32_e32 v56, v0
	v_mov_b32_e32 v57, v0
	v_mov_b32_e32 v58, v0
	v_mov_b32_e32 v59, v0
	v_mov_b32_e32 v60, v0
	v_mov_b32_e32 v61, v0
	v_mov_b32_e32 v62, v0
	v_mov_b32_e32 v63, v0
	v_mov_b32_e32 v64, v0
	v_mov_b32_e32 v65, v0
	v_mov_b32_e32 v66, v0
	v_mov_b32_e32 v67, v0
	v_mov_b32_e32 v68, v0
	v_mov_b32_e32 v69, v0
	v_mov_b32_e32 v70, v0
	v_mov_b32_e32 v71, v0
	v_mov_b32_e32 v80, v0
	v_mov_b32_e32 v81, v0
	v_mov_b32_e32 v82, v0
	v_mov_b32_e32 v83, v0
	v_mov_b32_e32 v84, v0
	v_mov_b32_e32 v85, v0
	v_mov_b32_e32 v86, v0
	v_mov_b32_e32 v87, v0
	v_mov_b32_e32 v96, v0
	v_mov_b32_e32 v97, v0
	v_mov_b32_e32 v98, v0
	v_mov_b32_e32 v99, v0
	v_mov_b32_e32 v100, v0
	v_mov_b32_e32 v101, v0
	v_mov_b32_e32 v102, v0
	v_mov_b32_e32 v103, v0
	v_mov_b32_e32 v112, v0
	v_mov_b32_e32 v113, v0
	v_mov_b32_e32 v114, v0
	v_mov_b32_e32 v115, v0
	v_mov_b32_e32 v116, v0
	v_mov_b32_e32 v117, v0
	v_mov_b32_e32 v118, v0
	v_mov_b32_e32 v119, v0
	v_mov_b32_e32 v72, v0
	v_mov_b32_e32 v73, v0
	v_mov_b32_e32 v74, v0
	v_mov_b32_e32 v75, v0
	v_mov_b32_e32 v76, v0
	v_mov_b32_e32 v77, v0
	v_mov_b32_e32 v78, v0
	v_mov_b32_e32 v79, v0
	v_mov_b32_e32 v88, v0
	v_mov_b32_e32 v89, v0
	v_mov_b32_e32 v90, v0
	v_mov_b32_e32 v91, v0
	v_mov_b32_e32 v92, v0
	v_mov_b32_e32 v93, v0
	v_mov_b32_e32 v94, v0
	v_mov_b32_e32 v95, v0
	v_mov_b32_e32 v104, v0
	v_mov_b32_e32 v105, v0
	v_mov_b32_e32 v106, v0
	v_mov_b32_e32 v107, v0
	v_mov_b32_e32 v108, v0
	v_mov_b32_e32 v109, v0
	v_mov_b32_e32 v110, v0
	v_mov_b32_e32 v111, v0
	v_mov_b32_e32 v120, v0
	v_mov_b32_e32 v121, v0
	v_mov_b32_e32 v122, v0
	v_mov_b32_e32 v123, v0
	v_mov_b32_e32 v124, v0
	v_mov_b32_e32 v125, v0
	v_mov_b32_e32 v126, v0
	v_mov_b32_e32 v127, v0
	.p2align 6

; template <class Epi, class Sched, bool ALIGN_EPI = false, bool SP2 = false>
; __device__ __forceinline__ void gemm_phase(LAS unsigned char* lds, const Gemm g, const Sched& S, const Epi& E, const int tid) {
;     ...
;     for (;;) {
;         const bool has_next = S.next(ui + 1, nxt);
;         const char* nA = has_next ? (const char*)g.A + (size_t)nxt.pm * tstep : cA; const char* nB = has_next ? (const char*)g.Bt + (size_t)nxt.pn * tstep : cB;
;         for (int t = 0; t < nt; t += 2) {
;             const bool last = (t == nt - 2);
;             const char* a1 = cA + (size_t)(t + 1) * kstep;
;             const char* a2 = last ? nA : cA + (size_t)(t + 2) * kstep; const char* b2 = last ? nB : cB + (size_t)(t + 2) * kstep;
;     ...
; #pragma unroll
;         for (int a = 0; a < 2; ++a)
; #pragma unroll
;             for (int b = 0; b < 2; ++b)
; #pragma unroll
;                 for (int m = 0; m < 4; ++m)
; #pragma unroll
;                     for (int n = 0; n < 2; ++n) acc[a][b][m][n] = (f32x4){0.f, 0.f, 0.f, 0.f};
;         cur = nxt; cA = nA; cB = nB; ++ui;
.LBB0_1410:
	s_ashr_i32 s15, s14, 31
	s_lshl_b64 s[16:17], s[14:15], 20
	s_add_u32 s16, s31, s16
	s_addc_u32 s17, s34, s17
	s_and_b64 s[18:19], s[2:3], exec
	s_cselect_b32 s1, s17, s21
	s_cselect_b32 s5, s16, s20
	s_ashr_i32 s13, s12, 31
	s_lshl_b64 s[18:19], s[12:13], 20
	s_add_u32 s18, s35, s18
	s_addc_u32 s19, s36, s19
	s_and_b64 s[24:25], s[2:3], exec
	s_cselect_b32 s13, s19, s23
	s_cselect_b32 s15, s18, s22
	s_add_u32 s20, s20, 0x80080
	s_addc_u32 s21, s21, 0
	s_add_u32 s46, s22, 0x100
	v_mov_b32_e32 v0, 0
	s_addc_u32 s47, s23, 0
	s_mov_b32 s48, -2
	v_mov_b32_e32 v1, v0
	v_mov_b32_e32 v2, v0
	v_mov_b32_e32 v3, v0
	v_mov_b32_e32 v4, v0
	v_mov_b32_e32 v5, v0
	v_mov_b32_e32 v6, v0
	v_mov_b32_e32 v7, v0
	v_mov_b32_e32 v16, v0
	v_mov_b32_e32 v17, v0
	v_mov_b32_e32 v18, v0
	v_mov_b32_e32 v19, v0
	v_mov_b32_e32 v20, v0
	v_mov_b32_e32 v21, v0
	v_mov_b32_e32 v22, v0
	v_mov_b32_e32 v23, v0
	v_mov_b32_e32 v32, v0
	v_mov_b32_e32 v33, v0
	v_mov_b32_e32 v34, v0
	v_mov_b32_e32 v35, v0
	v_mov_b32_e32 v36, v0
	v_mov_b32_e32 v37, v0
	v_mov_b32_e32 v38, v0
	v_mov_b32_e32 v39, v0
	v_mov_b32_e32 v48, v0
	v_mov_b32_e32 v49, v0
	s_waitcnt vmcnt(0)
	v_mov_b32_e32 v50, v0
	v_mov_b32_e32 v51, v0
	v_mov_b32_e32 v52, v0
	v_mov_b32_e32 v53, v0
	v_mov_b32_e32 v54, v0
	v_mov_b32_e32 v55, v0
	v_mov_b32_e32 v8, v0
	v_mov_b32_e32 v9, v0
	v_mov_b32_e32 v10, v0
	v_mov_b32_e32 v11, v0
	v_mov_b32_e32 v12, v0
	v_mov_b32_e32 v13, v0
	v_mov_b32_e32 v14, v0
	v_mov_b32_e32 v15, v0
	v_mov_b32_e32 v24, v0
	v_mov_b32_e32 v25, v0
	v_mov_b32_e32 v26, v0
	v_mov_b32_e32 v27, v0
	v_mov_b32_e32 v28, v0
	v_mov_b32_e32 v29, v0
	v_mov_b32_e32 v30, v0
	v_mov_b32_e32 v31, v0
	v_mov_b32_e32 v40, v0
	v_mov_b32_e32 v41, v0
	v_mov_b32_e32 v42, v0
	v_mov_b32_e32 v43, v0
	v_mov_b32_e32 v44, v0
	v_mov_b32_e32 v45, v0
	v_mov_b32_e32 v46, v0
	v_mov_b32_e32 v47, v0
	v_mov_b32_e32 v56, v0
	v_mov_b32_e32 v57, v0
	v_mov_b32_e32 v58, v0
	v_mov_b32_e32 v59, v0
	v_mov_b32_e32 v60, v0
	v_mov_b32_e32 v61, v0
	v_mov_b32_e32 v62, v0
	v_mov_b32_e32 v63, v0
	v_mov_b32_e32 v64, v0
	v_mov_b32_e32 v65, v0
	v_mov_b32_e32 v66, v0
	v_mov_b32_e32 v67, v0
	v_mov_b32_e32 v68, v0
	v_mov_b32_e32 v69, v0
	v_mov_b32_e32 v70, v0
	v_mov_b32_e32 v71, v0
	v_mov_b32_e32 v80, v0
	v_mov_b32_e32 v81, v0
	v_mov_b32_e32 v82, v0
	v_mov_b32_e32 v83, v0
	v_mov_b32_e32 v84, v0
	v_mov_b32_e32 v85, v0
	v_mov_b32_e32 v86, v0
	v_mov_b32_e32 v87, v0
	v_mov_b32_e32 v96, v0
	v_mov_b32_e32 v97, v0
	v_mov_b32_e32 v98, v0
	v_mov_b32_e32 v99, v0
	v_mov_b32_e32 v100, v0
	v_mov_b32_e32 v101, v0
	v_mov_b32_e32 v102, v0
	v_mov_b32_e32 v103, v0
	v_mov_b32_e32 v112, v0
	v_mov_b32_e32 v113, v0
	v_mov_b32_e32 v114, v0
	v_mov_b32_e32 v115, v0
	v_mov_b32_e32 v116, v0
	v_mov_b32_e32 v117, v0
	v_mov_b32_e32 v118, v0
	v_mov_b32_e32 v119, v0
	v_mov_b32_e32 v72, v0
	v_mov_b32_e32 v73, v0
	v_mov_b32_e32 v74, v0
	v_mov_b32_e32 v75, v0
	v_mov_b32_e32 v76, v0
	v_mov_b32_e32 v77, v0
	v_mov_b32_e32 v78, v0
	v_mov_b32_e32 v79, v0
	v_mov_b32_e32 v88, v0
	v_mov_b32_e32 v89, v0
	v_mov_b32_e32 v90, v0
	v_mov_b32_e32 v91, v0
	v_mov_b32_e32 v92, v0
	v_mov_b32_e32 v93, v0
	v_mov_b32_e32 v94, v0
	v_mov_b32_e32 v95, v0
	v_mov_b32_e32 v104, v0
	v_mov_b32_e32 v105, v0
	v_mov_b32_e32 v106, v0
	v_mov_b32_e32 v107, v0
	v_mov_b32_e32 v108, v0
	v_mov_b32_e32 v109, v0
	v_mov_b32_e32 v110, v0
	v_mov_b32_e32 v111, v0
	v_mov_b32_e32 v120, v0
	v_mov_b32_e32 v121, v0
	v_mov_b32_e32 v122, v0
	v_mov_b32_e32 v123, v0
	v_mov_b32_e32 v124, v0
	v_mov_b32_e32 v125, v0
	v_mov_b32_e32 v126, v0
	v_mov_b32_e32 v127, v0
	.p2align 6

; template <class Epi, class Sched, bool ALIGN_EPI = false, bool SP2 = false>
; __device__ __forceinline__ void gemm_phase(LAS unsigned char* lds, const Gemm g, const Sched& S, const Epi& E, const int tid) {
;     ...
;     for (;;) {
;         const bool has_next = S.next(ui + 1, nxt);
;         const char* nA = has_next ? (const char*)g.A + (size_t)nxt.pm * tstep : cA; const char* nB = has_next ? (const char*)g.Bt + (size_t)nxt.pn * tstep : cB;
;         for (int t = 0; t < nt; t += 2) {
;             const bool last = (t == nt - 2);
;             const char* a1 = cA + (size_t)(t + 1) * kstep;
;             const char* a2 = last ? nA : cA + (size_t)(t + 2) * kstep; const char* b2 = last ? nB : cB + (size_t)(t + 2) * kstep;
;     ...
; #pragma unroll
;         for (int a = 0; a < 2; ++a)
; #pragma unroll
;             for (int b = 0; b < 2; ++b)
; #pragma unroll
;                 for (int m = 0; m < 4; ++m)
; #pragma unroll
;                     for (int n = 0; n < 2; ++n) acc[a][b][m][n] = (f32x4){0.f, 0.f, 0.f, 0.f};
;         cur = nxt; cA = nA; cB = nB; ++ui;
.LBB0_1486:
	s_add_u32 s47, s16, 0x100
	v_mov_b32_e32 v0, 0
	s_addc_u32 s48, s17, 0
	s_mov_b32 s49, -2
	s_waitcnt lgkmcnt(0)
	v_mov_b32_e32 v1, v0
	v_mov_b32_e32 v2, v0
	v_mov_b32_e32 v3, v0
	v_mov_b32_e32 v4, v0
	v_mov_b32_e32 v5, v0
	v_mov_b32_e32 v6, v0
	v_mov_b32_e32 v7, v0
	v_mov_b32_e32 v16, v0
	v_mov_b32_e32 v17, v0
	v_mov_b32_e32 v18, v0
	v_mov_b32_e32 v19, v0
	v_mov_b32_e32 v20, v0
	v_mov_b32_e32 v21, v0
	v_mov_b32_e32 v22, v0
	v_mov_b32_e32 v23, v0
	v_mov_b32_e32 v32, v0
	v_mov_b32_e32 v33, v0
	v_mov_b32_e32 v34, v0
	v_mov_b32_e32 v35, v0
	v_mov_b32_e32 v36, v0
	v_mov_b32_e32 v37, v0
	v_mov_b32_e32 v38, v0
	v_mov_b32_e32 v39, v0
	v_mov_b32_e32 v48, v0
	v_mov_b32_e32 v49, v0
	v_mov_b32_e32 v50, v0
	v_mov_b32_e32 v51, v0
	v_mov_b32_e32 v52, v0
	v_mov_b32_e32 v53, v0
	v_mov_b32_e32 v54, v0
	v_mov_b32_e32 v55, v0
	v_mov_b32_e32 v8, v0
	v_mov_b32_e32 v9, v0
	v_mov_b32_e32 v10, v0
	v_mov_b32_e32 v11, v0
	v_mov_b32_e32 v12, v0
	v_mov_b32_e32 v13, v0
	v_mov_b32_e32 v14, v0
	v_mov_b32_e32 v15, v0
	v_mov_b32_e32 v24, v0
	v_mov_b32_e32 v25, v0
	v_mov_b32_e32 v26, v0
	v_mov_b32_e32 v27, v0
	v_mov_b32_e32 v28, v0
	v_mov_b32_e32 v29, v0
	v_mov_b32_e32 v30, v0
	v_mov_b32_e32 v31, v0
	v_mov_b32_e32 v40, v0
	v_mov_b32_e32 v41, v0
	v_mov_b32_e32 v42, v0
	v_mov_b32_e32 v43, v0
	v_mov_b32_e32 v44, v0
	v_mov_b32_e32 v45, v0
	v_mov_b32_e32 v46, v0
	v_mov_b32_e32 v47, v0
	v_mov_b32_e32 v56, v0
	v_mov_b32_e32 v57, v0
	v_mov_b32_e32 v58, v0
	v_mov_b32_e32 v59, v0
	v_mov_b32_e32 v60, v0
	v_mov_b32_e32 v61, v0
	v_mov_b32_e32 v62, v0
	v_mov_b32_e32 v63, v0
	v_mov_b32_e32 v64, v0
	v_mov_b32_e32 v65, v0
	v_mov_b32_e32 v66, v0
	v_mov_b32_e32 v67, v0
	v_mov_b32_e32 v68, v0
	v_mov_b32_e32 v69, v0
	v_mov_b32_e32 v70, v0
	v_mov_b32_e32 v71, v0
	v_mov_b32_e32 v80, v0
	v_mov_b32_e32 v81, v0
	v_mov_b32_e32 v82, v0
	v_mov_b32_e32 v83, v0
	v_mov_b32_e32 v84, v0
	v_mov_b32_e32 v85, v0
	v_mov_b32_e32 v86, v0
	v_mov_b32_e32 v87, v0
	v_mov_b32_e32 v96, v0
	v_mov_b32_e32 v97, v0
	v_mov_b32_e32 v98, v0
	v_mov_b32_e32 v99, v0
	v_mov_b32_e32 v100, v0
	v_mov_b32_e32 v101, v0
	v_mov_b32_e32 v102, v0
	v_mov_b32_e32 v103, v0
	v_mov_b32_e32 v112, v0
	v_mov_b32_e32 v113, v0
	v_mov_b32_e32 v114, v0
	v_mov_b32_e32 v115, v0
	v_mov_b32_e32 v116, v0
	v_mov_b32_e32 v117, v0
	v_mov_b32_e32 v118, v0
	v_mov_b32_e32 v119, v0
	v_mov_b32_e32 v72, v0
	v_mov_b32_e32 v73, v0
	v_mov_b32_e32 v74, v0
	v_mov_b32_e32 v75, v0
	v_mov_b32_e32 v76, v0
	v_mov_b32_e32 v77, v0
	v_mov_b32_e32 v78, v0
	v_mov_b32_e32 v79, v0
	v_mov_b32_e32 v88, v0
	v_mov_b32_e32 v89, v0
	v_mov_b32_e32 v90, v0
	v_mov_b32_e32 v91, v0
	v_mov_b32_e32 v92, v0
	v_mov_b32_e32 v93, v0
	v_mov_b32_e32 v94, v0
	v_mov_b32_e32 v95, v0
	v_mov_b32_e32 v104, v0
	v_mov_b32_e32 v105, v0
	v_mov_b32_e32 v106, v0
	v_mov_b32_e32 v107, v0
	v_mov_b32_e32 v108, v0
	v_mov_b32_e32 v109, v0
	v_mov_b32_e32 v110, v0
	v_mov_b32_e32 v111, v0
	v_mov_b32_e32 v120, v0
	v_mov_b32_e32 v121, v0
	v_mov_b32_e32 v122, v0
	v_mov_b32_e32 v123, v0
	v_mov_b32_e32 v124, v0
	v_mov_b32_e32 v125, v0
	v_mov_b32_e32 v126, v0
	v_mov_b32_e32 v127, v0
	.p2align 6
